# E10 + out-projection weight warm-up: each wave touches a 4 KB slice of the layer's bf16 w_out at the end of the mixers phase so the GEMM's first touches hit the last-level cache
# baseline (speedup 1.0000x reference)
; __device__ __forceinline__ unsigned cvt_pk_bf16(float lo, float hi) { f32x2_c v = {lo, hi}; bf16x2_c b = __builtin_convertvector(v, bf16x2_c); return __builtin_bit_cast(unsigned, b); }
; __device__ __forceinline__ float silu_f(float z) { return z * __builtin_amdgcn_rcpf(1.f + __expf(-z)); }
; __device__ __forceinline__ void la_store(const LA& st, bool use_sink, float sink2, const u32x2 (&zv)[8], bf16_t* yrow, int hi) {
;     float l = st.l; { auto rr = __builtin_amdgcn_permlane32_swap(__float_as_uint(l), __float_as_uint(l), false, false); l = __uint_as_float(rr[0]) + __uint_as_float(rr[1]); }
;     float inv;
;     if (use_sink) { const float m2 = fmaxf(st.m, sink2), a = __builtin_amdgcn_exp2f(st.m - m2); inv = a * __builtin_amdgcn_rcpf(l * a + __builtin_amdgcn_exp2f(sink2 - m2)); }
;     else inv = __builtin_amdgcn_rcpf(l);
; #pragma unroll
;     for (int db = 0; db < 2; ++db)
; #pragma unroll
;         for (int g = 0; g < 4; ++g) { const int c = 32 * db + 8 * g + 4 * hi; const u32x2 z = zv[4 * db + g];
;             const f32x16& o = db ? st.o1 : st.o0;
;             u32x2 w; w.x = cvt_pk_bf16(o[4 * g] * inv * silu_f(bf_lo(z.x)), o[4 * g + 1] * inv * silu_f(bf_hi(z.x)));
;             w.y = cvt_pk_bf16(o[4 * g + 2] * inv * silu_f(bf_lo(z.y)), o[4 * g + 3] * inv * silu_f(bf_hi(z.y)));
;             *(u32x2*)(yrow + c) = w; }
; __global__ void __launch_bounds__(NWAVES * 64, 2) mk_fwd(Args args) {
;     ...
;                 u32x2 zv[8];
;                 la_loadz(zv, PROJ + (size_t)tqa * PP + C_ZD + h * 64, hi); la_store(sa, false, 0.f, zv, Yb + (size_t)tqa * DMODEL + 1536 + h * 64, hi);
;                 la_loadz(zv, PROJ + (size_t)tqb * PP + C_ZD + h * 64, hi); la_store(sb, false, 0.f, zv, Yb + (size_t)tqb * DMODEL + 1536 + h * 64, hi);
.LBB0_708:
	v_mov_b32_e32 v145, v189
	v_lshl_add_u64 v[64:65], v[152:153], 0, v[144:145]
	s_mov_b64 s[4:5], 0x3000
	v_lshl_add_u64 v[68:69], v[64:65], 0, s[4:5]
	v_add_co_u32_e32 v64, vcc, 0x3000, v64
	v_ashrrev_i32_e32 v149, 31, v148
	s_nop 0
	v_addc_co_u32_e32 v65, vcc, 0, v65, vcc
	global_load_dwordx2 v[80:81], v[64:65], off
	global_load_dwordx2 v[78:79], v[68:69], off offset:16
	global_load_dwordx2 v[76:77], v[68:69], off offset:32
	global_load_dwordx2 v[74:75], v[68:69], off offset:48
	global_load_dwordx2 v[72:73], v[68:69], off offset:64
	global_load_dwordx2 v[70:71], v[68:69], off offset:80
	global_load_dwordx2 v[66:67], v[68:69], off offset:96
	global_load_dwordx2 v[64:65], v[68:69], off offset:112
	v_lshlrev_b64 v[68:69], 12, v[150:151]
	v_lshl_add_u64 v[68:69], s[42:43], 0, v[68:69]
	v_lshl_add_u64 v[82:83], v[68:69], 0, s[70:71]
	v_mov_b32_e32 v68, v158
	s_nop 1
	v_permlane32_swap_b32_e32 v158, v68
	v_add_f32_e32 v68, v158, v68
	v_rcp_f32_e32 v68, v68
	v_readlane_b32 s26, v255, 40
	v_readlane_b32 s27, v255, 41
	s_mov_b32 s28, s76
	s_mov_b64 s[40:41], 0x800
	s_mov_b32 s36, s77
	s_waitcnt vmcnt(7)
	v_lshlrev_b32_e32 v84, 16, v80
	v_mul_f32_e32 v69, 0xbfb8aa3b, v84
	v_exp_f32_e32 v69, v69
	v_and_b32_e32 v85, 0xffff0000, v80
	v_add_f32_e32 v69, 1.0, v69
	v_rcp_f32_e32 v86, v69
	v_pk_mul_f32 v[32:33], v[32:33], v[68:69] op_sel_hi:[1,0]
	v_mul_f32_e32 v69, 0xbfb8aa3b, v85
	v_exp_f32_e32 v69, v69
	s_nop 0
	v_add_f32_e32 v69, 1.0, v69
	v_rcp_f32_e32 v87, v69
	s_nop 0
	v_pk_mul_f32 v[84:85], v[86:87], v[84:85]
	s_nop 0
	v_pk_mul_f32 v[32:33], v[84:85], v[32:33]
	s_nop 0
	v_cvt_pk_bf16_f32 v80, v32, v33
	v_lshlrev_b32_e32 v32, 16, v81
	v_mul_f32_e32 v69, 0xbfb8aa3b, v32
	v_exp_f32_e32 v69, v69
	v_and_b32_e32 v33, 0xffff0000, v81
	v_add_f32_e32 v69, 1.0, v69
	v_rcp_f32_e32 v84, v69
	v_pk_mul_f32 v[34:35], v[34:35], v[68:69] op_sel_hi:[1,0]
	v_mul_f32_e32 v69, 0xbfb8aa3b, v33
	v_exp_f32_e32 v69, v69
	s_nop 0
	v_add_f32_e32 v69, 1.0, v69
	v_rcp_f32_e32 v85, v69
	s_nop 0
	v_pk_mul_f32 v[32:33], v[84:85], v[32:33]
	s_nop 0
	v_pk_mul_f32 v[32:33], v[32:33], v[34:35]
	s_waitcnt vmcnt(6)
	v_lshlrev_b32_e32 v34, 16, v78
	v_mul_f32_e32 v69, 0xbfb8aa3b, v34
	v_exp_f32_e32 v69, v69
	v_cvt_pk_bf16_f32 v81, v32, v33
	v_lshl_add_u64 v[32:33], v[82:83], 0, v[144:145]
	v_and_b32_e32 v35, 0xffff0000, v78
	v_add_f32_e32 v69, 1.0, v69
	global_store_dwordx2 v[32:33], v[80:81], off offset:3072
	v_rcp_f32_e32 v80, v69
	v_pk_mul_f32 v[36:37], v[36:37], v[68:69] op_sel_hi:[1,0]
	v_mul_f32_e32 v69, 0xbfb8aa3b, v35
	v_exp_f32_e32 v69, v69
	s_nop 0
	v_add_f32_e32 v69, 1.0, v69
	v_rcp_f32_e32 v81, v69
	v_pk_mul_f32 v[38:39], v[38:39], v[68:69] op_sel_hi:[1,0]
	v_pk_mul_f32 v[16:17], v[16:17], v[68:69] op_sel_hi:[1,0]
	v_pk_mul_f32 v[18:19], v[18:19], v[68:69] op_sel_hi:[1,0]
	v_pk_mul_f32 v[34:35], v[80:81], v[34:35]
	v_pk_mul_f32 v[20:21], v[20:21], v[68:69] op_sel_hi:[1,0]
	v_pk_mul_f32 v[34:35], v[34:35], v[36:37]
	v_lshlrev_b32_e32 v36, 16, v79
	v_cvt_pk_bf16_f32 v34, v34, v35
	v_mul_f32_e32 v35, 0xbfb8aa3b, v36
	v_exp_f32_e32 v35, v35
	v_and_b32_e32 v37, 0xffff0000, v79
	v_pk_mul_f32 v[22:23], v[22:23], v[68:69] op_sel_hi:[1,0]
	v_add_f32_e32 v35, 1.0, v35
	v_rcp_f32_e32 v78, v35
	v_mul_f32_e32 v35, 0xbfb8aa3b, v37
	v_exp_f32_e32 v35, v35
	s_nop 0
	v_add_f32_e32 v35, 1.0, v35
	v_rcp_f32_e32 v79, v35
	s_nop 0
	v_pk_mul_f32 v[36:37], v[78:79], v[36:37]
	s_nop 0
	v_pk_mul_f32 v[36:37], v[36:37], v[38:39]
	v_pk_mul_f32 v[38:39], v[40:41], v[68:69] op_sel_hi:[1,0]
	v_cvt_pk_bf16_f32 v35, v36, v37
	global_store_dwordx2 v[32:33], v[34:35], off offset:3088
	s_waitcnt vmcnt(7)
	v_lshlrev_b32_e32 v34, 16, v76
	v_and_b32_e32 v35, 0xffff0000, v76
	v_mul_f32_e32 v36, 0xbfb8aa3b, v34
	v_mul_f32_e32 v37, 0xbfb8aa3b, v35
	v_exp_f32_e32 v36, v36
	v_exp_f32_e32 v37, v37
	v_pk_mul_f32 v[40:41], v[42:43], v[68:69] op_sel_hi:[1,0]
	v_add_f32_e32 v36, 1.0, v36
	v_add_f32_e32 v37, 1.0, v37
	v_rcp_f32_e32 v36, v36
	v_rcp_f32_e32 v37, v37
	s_nop 0
	v_pk_mul_f32 v[34:35], v[36:37], v[34:35]
	s_nop 0
	v_pk_mul_f32 v[34:35], v[34:35], v[38:39]
	v_lshlrev_b32_e32 v36, 16, v77
	v_cvt_pk_bf16_f32 v34, v34, v35
	v_mul_f32_e32 v35, 0xbfb8aa3b, v36
	v_exp_f32_e32 v35, v35
	v_and_b32_e32 v37, 0xffff0000, v77
	v_add_f32_e32 v35, 1.0, v35
	v_rcp_f32_e32 v38, v35
	v_mul_f32_e32 v35, 0xbfb8aa3b, v37
	v_exp_f32_e32 v35, v35
	s_nop 0
	v_add_f32_e32 v35, 1.0, v35
	v_rcp_f32_e32 v39, v35
	s_nop 0
	v_pk_mul_f32 v[36:37], v[38:39], v[36:37]
	s_nop 0
	v_pk_mul_f32 v[36:37], v[36:37], v[40:41]
	v_pk_mul_f32 v[38:39], v[44:45], v[68:69] op_sel_hi:[1,0]
	v_cvt_pk_bf16_f32 v35, v36, v37
	global_store_dwordx2 v[32:33], v[34:35], off offset:3104
	s_waitcnt vmcnt(7)
	v_lshlrev_b32_e32 v34, 16, v74
	v_and_b32_e32 v35, 0xffff0000, v74
	v_mul_f32_e32 v36, 0xbfb8aa3b, v34
	v_mul_f32_e32 v37, 0xbfb8aa3b, v35
	v_exp_f32_e32 v36, v36
	v_exp_f32_e32 v37, v37
	v_pk_mul_f32 v[40:41], v[46:47], v[68:69] op_sel_hi:[1,0]
	v_add_f32_e32 v36, 1.0, v36
	v_add_f32_e32 v37, 1.0, v37
	v_rcp_f32_e32 v36, v36
	v_rcp_f32_e32 v37, v37
	s_nop 0
	v_pk_mul_f32 v[34:35], v[36:37], v[34:35]
	s_nop 0
	v_pk_mul_f32 v[34:35], v[34:35], v[38:39]
	v_lshlrev_b32_e32 v36, 16, v75
	v_cvt_pk_bf16_f32 v34, v34, v35
	v_mul_f32_e32 v35, 0xbfb8aa3b, v36
	v_exp_f32_e32 v35, v35
	v_and_b32_e32 v37, 0xffff0000, v75
	v_add_f32_e32 v35, 1.0, v35
	v_rcp_f32_e32 v38, v35
	v_mul_f32_e32 v35, 0xbfb8aa3b, v37
	v_exp_f32_e32 v35, v35
	s_nop 0
	v_add_f32_e32 v35, 1.0, v35
	v_rcp_f32_e32 v39, v35
	s_nop 0
	v_pk_mul_f32 v[36:37], v[38:39], v[36:37]
	s_nop 0
	v_pk_mul_f32 v[36:37], v[36:37], v[40:41]
	s_nop 0
	v_cvt_pk_bf16_f32 v35, v36, v37
	global_store_dwordx2 v[32:33], v[34:35], off offset:3120
	s_waitcnt vmcnt(7)
; __device__ __forceinline__ unsigned cvt_pk_bf16(float lo, float hi) { f32x2_c v = {lo, hi}; bf16x2_c b = __builtin_convertvector(v, bf16x2_c); return __builtin_bit_cast(unsigned, b); }
; __device__ __forceinline__ float silu_f(float z) { return z * __builtin_amdgcn_rcpf(1.f + __expf(-z)); }
; __device__ __forceinline__ void la_store(const LA& st, bool use_sink, float sink2, const u32x2 (&zv)[8], bf16_t* yrow, int hi) {
;     float l = st.l; { auto rr = __builtin_amdgcn_permlane32_swap(__float_as_uint(l), __float_as_uint(l), false, false); l = __uint_as_float(rr[0]) + __uint_as_float(rr[1]); }
;     float inv;
;     if (use_sink) { const float m2 = fmaxf(st.m, sink2), a = __builtin_amdgcn_exp2f(st.m - m2); inv = a * __builtin_amdgcn_rcpf(l * a + __builtin_amdgcn_exp2f(sink2 - m2)); }
;     else inv = __builtin_amdgcn_rcpf(l);
; #pragma unroll
;     for (int db = 0; db < 2; ++db)
; #pragma unroll
;         for (int g = 0; g < 4; ++g) { const int c = 32 * db + 8 * g + 4 * hi; const u32x2 z = zv[4 * db + g];
;             const f32x16& o = db ? st.o1 : st.o0;
;             u32x2 w; w.x = cvt_pk_bf16(o[4 * g] * inv * silu_f(bf_lo(z.x)), o[4 * g + 1] * inv * silu_f(bf_hi(z.x)));
;             w.y = cvt_pk_bf16(o[4 * g + 2] * inv * silu_f(bf_lo(z.y)), o[4 * g + 3] * inv * silu_f(bf_hi(z.y)));
;             *(u32x2*)(yrow + c) = w; }
; __global__ void __launch_bounds__(NWAVES * 64, 2) mk_fwd(Args args) {
;     ...
;                 u32x2 zv[8];
;                 la_loadz(zv, PROJ + (size_t)tqa * PP + C_ZD + h * 64, hi); la_store(sa, false, 0.f, zv, Yb + (size_t)tqa * DMODEL + 1536 + h * 64, hi);
;                 la_loadz(zv, PROJ + (size_t)tqb * PP + C_ZD + h * 64, hi); la_store(sb, false, 0.f, zv, Yb + (size_t)tqb * DMODEL + 1536 + h * 64, hi);
	v_lshlrev_b32_e32 v34, 16, v72
	v_and_b32_e32 v35, 0xffff0000, v72
	v_mul_f32_e32 v36, 0xbfb8aa3b, v34
	v_mul_f32_e32 v37, 0xbfb8aa3b, v35
	v_exp_f32_e32 v36, v36
	v_exp_f32_e32 v37, v37
	v_add_f32_e32 v36, 1.0, v36
	v_add_f32_e32 v37, 1.0, v37
	v_rcp_f32_e32 v36, v36
	v_rcp_f32_e32 v37, v37
	s_nop 0
	v_pk_mul_f32 v[34:35], v[36:37], v[34:35]
	s_nop 0
	v_pk_mul_f32 v[16:17], v[34:35], v[16:17]
	v_lshlrev_b32_e32 v34, 16, v73
	v_cvt_pk_bf16_f32 v16, v16, v17
	v_mul_f32_e32 v17, 0xbfb8aa3b, v34
	v_exp_f32_e32 v17, v17
	v_and_b32_e32 v35, 0xffff0000, v73
	v_add_f32_e32 v17, 1.0, v17
	v_rcp_f32_e32 v36, v17
	v_mul_f32_e32 v17, 0xbfb8aa3b, v35
	v_exp_f32_e32 v17, v17
	s_nop 0
	v_add_f32_e32 v17, 1.0, v17
	v_rcp_f32_e32 v37, v17
	s_nop 0
	v_pk_mul_f32 v[34:35], v[36:37], v[34:35]
	s_nop 0
	v_pk_mul_f32 v[18:19], v[34:35], v[18:19]
	s_nop 0
	v_cvt_pk_bf16_f32 v17, v18, v19
	global_store_dwordx2 v[32:33], v[16:17], off offset:3136
	s_waitcnt vmcnt(7)
	v_lshlrev_b32_e32 v16, 16, v70
	v_and_b32_e32 v17, 0xffff0000, v70
	v_mul_f32_e32 v18, 0xbfb8aa3b, v16
	v_mul_f32_e32 v19, 0xbfb8aa3b, v17
	v_exp_f32_e32 v18, v18
	v_exp_f32_e32 v19, v19
	v_add_f32_e32 v18, 1.0, v18
	v_add_f32_e32 v19, 1.0, v19
	v_rcp_f32_e32 v18, v18
	v_rcp_f32_e32 v19, v19
	s_nop 0
	v_pk_mul_f32 v[16:17], v[18:19], v[16:17]
	s_nop 0
	v_pk_mul_f32 v[16:17], v[20:21], v[16:17]
	v_lshlrev_b32_e32 v18, 16, v71
	v_cvt_pk_bf16_f32 v16, v16, v17
	v_mul_f32_e32 v17, 0xbfb8aa3b, v18
	v_exp_f32_e32 v17, v17
	v_and_b32_e32 v19, 0xffff0000, v71
	v_add_f32_e32 v17, 1.0, v17
	v_rcp_f32_e32 v20, v17
	v_mul_f32_e32 v17, 0xbfb8aa3b, v19
	v_exp_f32_e32 v17, v17
	s_nop 0
	v_add_f32_e32 v17, 1.0, v17
	v_rcp_f32_e32 v21, v17
	s_nop 0
	v_pk_mul_f32 v[18:19], v[20:21], v[18:19]
	s_nop 0
	v_pk_mul_f32 v[18:19], v[22:23], v[18:19]
	v_pk_mul_f32 v[20:21], v[24:25], v[68:69] op_sel_hi:[1,0]
	v_cvt_pk_bf16_f32 v17, v18, v19
	global_store_dwordx2 v[32:33], v[16:17], off offset:3152
	s_waitcnt vmcnt(7)
	v_lshlrev_b32_e32 v16, 16, v66
	v_and_b32_e32 v17, 0xffff0000, v66
	v_mul_f32_e32 v18, 0xbfb8aa3b, v16
	v_mul_f32_e32 v19, 0xbfb8aa3b, v17
	v_exp_f32_e32 v18, v18
	v_exp_f32_e32 v19, v19
	v_pk_mul_f32 v[22:23], v[26:27], v[68:69] op_sel_hi:[1,0]
	v_add_f32_e32 v18, 1.0, v18
	v_add_f32_e32 v19, 1.0, v19
	v_rcp_f32_e32 v18, v18
	v_rcp_f32_e32 v19, v19
	s_nop 0
	v_pk_mul_f32 v[16:17], v[18:19], v[16:17]
	s_nop 0
	v_pk_mul_f32 v[16:17], v[20:21], v[16:17]
	v_lshlrev_b32_e32 v18, 16, v67
	v_cvt_pk_bf16_f32 v16, v16, v17
	v_mul_f32_e32 v17, 0xbfb8aa3b, v18
	v_exp_f32_e32 v17, v17
	v_and_b32_e32 v19, 0xffff0000, v67
	v_add_f32_e32 v17, 1.0, v17
	v_rcp_f32_e32 v20, v17
	v_mul_f32_e32 v17, 0xbfb8aa3b, v19
	v_exp_f32_e32 v17, v17
	s_nop 0
	v_add_f32_e32 v17, 1.0, v17
	v_rcp_f32_e32 v21, v17
	s_nop 0
	v_pk_mul_f32 v[18:19], v[20:21], v[18:19]
	s_nop 0
	v_pk_mul_f32 v[18:19], v[22:23], v[18:19]
	v_pk_mul_f32 v[20:21], v[28:29], v[68:69] op_sel_hi:[1,0]
	v_cvt_pk_bf16_f32 v17, v18, v19
	global_store_dwordx2 v[32:33], v[16:17], off offset:3168
	s_waitcnt vmcnt(7)
	v_lshlrev_b32_e32 v16, 16, v64
	v_and_b32_e32 v17, 0xffff0000, v64
	v_mul_f32_e32 v18, 0xbfb8aa3b, v16
	v_mul_f32_e32 v19, 0xbfb8aa3b, v17
	v_exp_f32_e32 v18, v18
	v_exp_f32_e32 v19, v19
	v_pk_mul_f32 v[22:23], v[30:31], v[68:69] op_sel_hi:[1,0]
	v_add_f32_e32 v18, 1.0, v18
	v_add_f32_e32 v19, 1.0, v19
	v_rcp_f32_e32 v18, v18
	v_rcp_f32_e32 v19, v19
	s_nop 0
	v_pk_mul_f32 v[16:17], v[18:19], v[16:17]
	s_nop 0
	v_pk_mul_f32 v[16:17], v[20:21], v[16:17]
	v_lshlrev_b32_e32 v18, 16, v65
	v_cvt_pk_bf16_f32 v16, v16, v17
	v_mul_f32_e32 v17, 0xbfb8aa3b, v18
	v_exp_f32_e32 v17, v17
	v_and_b32_e32 v19, 0xffff0000, v65
	v_add_f32_e32 v17, 1.0, v17
	v_rcp_f32_e32 v20, v17
	v_mul_f32_e32 v17, 0xbfb8aa3b, v19
	v_exp_f32_e32 v17, v17
	s_nop 0
	v_add_f32_e32 v17, 1.0, v17
	v_rcp_f32_e32 v21, v17
	s_nop 0
	v_pk_mul_f32 v[18:19], v[20:21], v[18:19]
	s_nop 0
	v_pk_mul_f32 v[18:19], v[22:23], v[18:19]
	s_nop 0
	v_cvt_pk_bf16_f32 v17, v18, v19
	global_store_dwordx2 v[32:33], v[16:17], off offset:3184
	v_mov_b64_e32 v[16:17], s[74:75]
	v_mad_i64_i32 v[16:17], s[0:1], v148, s64, v[16:17]
	v_lshl_add_u64 v[16:17], v[16:17], 0, s[70:71]
	v_lshl_add_u64 v[18:19], v[16:17], 0, v[144:145]
	s_movk_i32 s0, 0x3000
	v_lshl_add_u64 v[16:17], v[18:19], 0, s[4:5]
	v_add_co_u32_e32 v18, vcc, s0, v18
	s_nop 1
	v_addc_co_u32_e32 v19, vcc, 0, v19, vcc
	global_load_dwordx2 v[20:21], v[18:19], off
	global_load_dwordx2 v[32:33], v[16:17], off offset:16
	global_load_dwordx2 v[30:31], v[16:17], off offset:32
	global_load_dwordx2 v[28:29], v[16:17], off offset:48
	global_load_dwordx2 v[26:27], v[16:17], off offset:64
	global_load_dwordx2 v[24:25], v[16:17], off offset:80
	global_load_dwordx2 v[22:23], v[16:17], off offset:96
	s_nop 0
	global_load_dwordx2 v[16:17], v[16:17], off offset:112
	v_lshlrev_b64 v[18:19], 12, v[148:149]
	v_lshl_add_u64 v[18:19], s[42:43], 0, v[18:19]
	v_lshl_add_u64 v[34:35], v[18:19], 0, s[70:71]
	v_mov_b32_e32 v18, v156
	s_nop 1
	v_permlane32_swap_b32_e32 v156, v18
	v_add_f32_e32 v18, v156, v18
	v_rcp_f32_e32 v18, v18
	s_waitcnt vmcnt(7)
	v_lshlrev_b32_e32 v36, 16, v20
	v_mul_f32_e32 v19, 0xbfb8aa3b, v36
	v_exp_f32_e32 v19, v19
	v_and_b32_e32 v37, 0xffff0000, v20
	v_lshlrev_b32_e32 v20, 16, v21
	v_and_b32_e32 v21, 0xffff0000, v21
	v_add_f32_e32 v19, 1.0, v19
	v_rcp_f32_e32 v38, v19
	v_pk_mul_f32 v[40:41], v[48:49], v[18:19] op_sel_hi:[1,0]
	v_mul_f32_e32 v19, 0xbfb8aa3b, v37
	v_exp_f32_e32 v19, v19
	s_nop 0
	v_add_f32_e32 v19, 1.0, v19
	v_rcp_f32_e32 v39, v19
	v_mul_f32_e32 v19, 0xbfb8aa3b, v20
	v_exp_f32_e32 v19, v19
	v_pk_mul_f32 v[36:37], v[38:39], v[36:37]
	s_nop 0
	v_pk_mul_f32 v[36:37], v[36:37], v[40:41]
	v_add_f32_e32 v19, 1.0, v19
	v_rcp_f32_e32 v38, v19
	v_pk_mul_f32 v[40:41], v[50:51], v[18:19] op_sel_hi:[1,0]
	v_mul_f32_e32 v19, 0xbfb8aa3b, v21
	v_exp_f32_e32 v19, v19
	v_cvt_pk_bf16_f32 v36, v36, v37
	v_add_f32_e32 v19, 1.0, v19
	v_rcp_f32_e32 v39, v19
	s_nop 0
	v_pk_mul_f32 v[20:21], v[38:39], v[20:21]
	s_nop 0
	v_pk_mul_f32 v[20:21], v[20:21], v[40:41]
	s_nop 0
	v_cvt_pk_bf16_f32 v37, v20, v21
	v_lshl_add_u64 v[20:21], v[34:35], 0, v[144:145]
	s_waitcnt vmcnt(6)
; __device__ __forceinline__ unsigned cvt_pk_bf16(float lo, float hi) { f32x2_c v = {lo, hi}; bf16x2_c b = __builtin_convertvector(v, bf16x2_c); return __builtin_bit_cast(unsigned, b); }
; __device__ __forceinline__ float silu_f(float z) { return z * __builtin_amdgcn_rcpf(1.f + __expf(-z)); }
; __device__ __forceinline__ void la_store(const LA& st, bool use_sink, float sink2, const u32x2 (&zv)[8], bf16_t* yrow, int hi) {
;     float l = st.l; { auto rr = __builtin_amdgcn_permlane32_swap(__float_as_uint(l), __float_as_uint(l), false, false); l = __uint_as_float(rr[0]) + __uint_as_float(rr[1]); }
;     float inv;
;     if (use_sink) { const float m2 = fmaxf(st.m, sink2), a = __builtin_amdgcn_exp2f(st.m - m2); inv = a * __builtin_amdgcn_rcpf(l * a + __builtin_amdgcn_exp2f(sink2 - m2)); }
;     else inv = __builtin_amdgcn_rcpf(l);
; #pragma unroll
;     for (int db = 0; db < 2; ++db)
; #pragma unroll
;         for (int g = 0; g < 4; ++g) { const int c = 32 * db + 8 * g + 4 * hi; const u32x2 z = zv[4 * db + g];
;             const f32x16& o = db ? st.o1 : st.o0;
;             u32x2 w; w.x = cvt_pk_bf16(o[4 * g] * inv * silu_f(bf_lo(z.x)), o[4 * g + 1] * inv * silu_f(bf_hi(z.x)));
;             w.y = cvt_pk_bf16(o[4 * g + 2] * inv * silu_f(bf_lo(z.y)), o[4 * g + 3] * inv * silu_f(bf_hi(z.y)));
;             *(u32x2*)(yrow + c) = w; }
	v_lshlrev_b32_e32 v34, 16, v32
	v_mul_f32_e32 v19, 0xbfb8aa3b, v34
	v_exp_f32_e32 v19, v19
	v_and_b32_e32 v35, 0xffff0000, v32
	global_store_dwordx2 v[20:21], v[36:37], off offset:3072
	v_add_f32_e32 v19, 1.0, v19
	v_rcp_f32_e32 v36, v19
	v_pk_mul_f32 v[38:39], v[52:53], v[18:19] op_sel_hi:[1,0]
	v_mul_f32_e32 v19, 0xbfb8aa3b, v35
	v_exp_f32_e32 v19, v19
	s_nop 0
	v_add_f32_e32 v19, 1.0, v19
	v_rcp_f32_e32 v37, v19
	s_nop 0
	v_pk_mul_f32 v[34:35], v[36:37], v[34:35]
	s_nop 0
	v_pk_mul_f32 v[34:35], v[34:35], v[38:39]
	s_nop 0
	v_cvt_pk_bf16_f32 v32, v34, v35
	v_lshlrev_b32_e32 v34, 16, v33
	v_mul_f32_e32 v19, 0xbfb8aa3b, v34
	v_exp_f32_e32 v19, v19
	v_and_b32_e32 v35, 0xffff0000, v33
	v_add_f32_e32 v19, 1.0, v19
	v_rcp_f32_e32 v36, v19
	v_pk_mul_f32 v[38:39], v[54:55], v[18:19] op_sel_hi:[1,0]
	v_mul_f32_e32 v19, 0xbfb8aa3b, v35
	v_exp_f32_e32 v19, v19
	s_nop 0
	v_add_f32_e32 v19, 1.0, v19
	v_rcp_f32_e32 v37, v19
	s_nop 0
	v_pk_mul_f32 v[34:35], v[36:37], v[34:35]
	s_nop 0
	v_pk_mul_f32 v[34:35], v[34:35], v[38:39]
	s_nop 0
	v_cvt_pk_bf16_f32 v33, v34, v35
	global_store_dwordx2 v[20:21], v[32:33], off offset:3088
	s_waitcnt vmcnt(7)
	v_lshlrev_b32_e32 v32, 16, v30
	v_mul_f32_e32 v19, 0xbfb8aa3b, v32
	v_exp_f32_e32 v19, v19
	v_and_b32_e32 v33, 0xffff0000, v30
	v_add_f32_e32 v19, 1.0, v19
	v_rcp_f32_e32 v34, v19
	v_pk_mul_f32 v[36:37], v[56:57], v[18:19] op_sel_hi:[1,0]
	v_mul_f32_e32 v19, 0xbfb8aa3b, v33
	v_exp_f32_e32 v19, v19
	s_nop 0
	v_add_f32_e32 v19, 1.0, v19
	v_rcp_f32_e32 v35, v19
	s_nop 0
	v_pk_mul_f32 v[32:33], v[34:35], v[32:33]
	s_nop 0
	v_pk_mul_f32 v[32:33], v[32:33], v[36:37]
	s_nop 0
	v_cvt_pk_bf16_f32 v30, v32, v33
	v_lshlrev_b32_e32 v32, 16, v31
	v_mul_f32_e32 v19, 0xbfb8aa3b, v32
	v_exp_f32_e32 v19, v19
	v_and_b32_e32 v33, 0xffff0000, v31
	v_add_f32_e32 v19, 1.0, v19
	v_rcp_f32_e32 v34, v19
	v_pk_mul_f32 v[36:37], v[58:59], v[18:19] op_sel_hi:[1,0]
	v_mul_f32_e32 v19, 0xbfb8aa3b, v33
	v_exp_f32_e32 v19, v19
	s_nop 0
	v_add_f32_e32 v19, 1.0, v19
	v_rcp_f32_e32 v35, v19
	s_nop 0
	v_pk_mul_f32 v[32:33], v[34:35], v[32:33]
	s_nop 0
	v_pk_mul_f32 v[32:33], v[32:33], v[36:37]
	s_nop 0
	v_cvt_pk_bf16_f32 v31, v32, v33
	global_store_dwordx2 v[20:21], v[30:31], off offset:3104
	s_waitcnt vmcnt(7)
	v_lshlrev_b32_e32 v30, 16, v28
	v_mul_f32_e32 v19, 0xbfb8aa3b, v30
	v_exp_f32_e32 v19, v19
	v_and_b32_e32 v31, 0xffff0000, v28
	v_add_f32_e32 v19, 1.0, v19
	v_rcp_f32_e32 v32, v19
	v_pk_mul_f32 v[34:35], v[60:61], v[18:19] op_sel_hi:[1,0]
	v_mul_f32_e32 v19, 0xbfb8aa3b, v31
	v_exp_f32_e32 v19, v19
	s_nop 0
	v_add_f32_e32 v19, 1.0, v19
	v_rcp_f32_e32 v33, v19
	s_nop 0
	v_pk_mul_f32 v[30:31], v[32:33], v[30:31]
	s_nop 0
	v_pk_mul_f32 v[30:31], v[30:31], v[34:35]
	s_nop 0
	v_cvt_pk_bf16_f32 v28, v30, v31
	v_lshlrev_b32_e32 v30, 16, v29
	v_mul_f32_e32 v19, 0xbfb8aa3b, v30
	v_exp_f32_e32 v19, v19
	v_and_b32_e32 v31, 0xffff0000, v29
	v_add_f32_e32 v19, 1.0, v19
	v_rcp_f32_e32 v32, v19
	v_pk_mul_f32 v[34:35], v[62:63], v[18:19] op_sel_hi:[1,0]
	v_mul_f32_e32 v19, 0xbfb8aa3b, v31
	v_exp_f32_e32 v19, v19
	s_nop 0
	v_add_f32_e32 v19, 1.0, v19
	v_rcp_f32_e32 v33, v19
	s_nop 0
	v_pk_mul_f32 v[30:31], v[32:33], v[30:31]
	s_nop 0
	v_pk_mul_f32 v[30:31], v[30:31], v[34:35]
	s_nop 0
	v_cvt_pk_bf16_f32 v29, v30, v31
	global_store_dwordx2 v[20:21], v[28:29], off offset:3120
	s_waitcnt vmcnt(7)
	v_lshlrev_b32_e32 v28, 16, v26
	v_mul_f32_e32 v19, 0xbfb8aa3b, v28
	v_exp_f32_e32 v19, v19
	v_and_b32_e32 v29, 0xffff0000, v26
	v_lshlrev_b32_e32 v26, 16, v27
	v_and_b32_e32 v27, 0xffff0000, v27
	v_add_f32_e32 v19, 1.0, v19
	v_rcp_f32_e32 v30, v19
	v_pk_mul_f32 v[0:1], v[0:1], v[18:19] op_sel_hi:[1,0]
	v_mul_f32_e32 v19, 0xbfb8aa3b, v29
	v_exp_f32_e32 v19, v19
	s_nop 0
	v_add_f32_e32 v19, 1.0, v19
	v_rcp_f32_e32 v31, v19
	v_pk_mul_f32 v[2:3], v[2:3], v[18:19] op_sel_hi:[1,0]
	v_pk_mul_f32 v[4:5], v[4:5], v[18:19] op_sel_hi:[1,0]
	v_pk_mul_f32 v[6:7], v[6:7], v[18:19] op_sel_hi:[1,0]
	v_pk_mul_f32 v[28:29], v[30:31], v[28:29]
	s_nop 0
	v_pk_mul_f32 v[0:1], v[28:29], v[0:1]
	s_nop 0
	v_cvt_pk_bf16_f32 v0, v0, v1
	v_mul_f32_e32 v1, 0xbfb8aa3b, v26
	v_exp_f32_e32 v1, v1
	s_nop 0
	v_add_f32_e32 v1, 1.0, v1
	v_rcp_f32_e32 v28, v1
	v_mul_f32_e32 v1, 0xbfb8aa3b, v27
	v_exp_f32_e32 v1, v1
	s_nop 0
	v_add_f32_e32 v1, 1.0, v1
	v_rcp_f32_e32 v29, v1
	s_nop 0
	v_pk_mul_f32 v[26:27], v[28:29], v[26:27]
	s_nop 0
	v_pk_mul_f32 v[2:3], v[26:27], v[2:3]
	s_nop 0
	v_cvt_pk_bf16_f32 v1, v2, v3
	global_store_dwordx2 v[20:21], v[0:1], off offset:3136
	s_waitcnt vmcnt(7)
; __device__ __forceinline__ unsigned cvt_pk_bf16(float lo, float hi) { f32x2_c v = {lo, hi}; bf16x2_c b = __builtin_convertvector(v, bf16x2_c); return __builtin_bit_cast(unsigned, b); }
; __device__ __forceinline__ float silu_f(float z) { return z * __builtin_amdgcn_rcpf(1.f + __expf(-z)); }
; __device__ __forceinline__ void la_store(const LA& st, bool use_sink, float sink2, const u32x2 (&zv)[8], bf16_t* yrow, int hi) {
;     float l = st.l; { auto rr = __builtin_amdgcn_permlane32_swap(__float_as_uint(l), __float_as_uint(l), false, false); l = __uint_as_float(rr[0]) + __uint_as_float(rr[1]); }
;     float inv;
;     if (use_sink) { const float m2 = fmaxf(st.m, sink2), a = __builtin_amdgcn_exp2f(st.m - m2); inv = a * __builtin_amdgcn_rcpf(l * a + __builtin_amdgcn_exp2f(sink2 - m2)); }
;     else inv = __builtin_amdgcn_rcpf(l);
; #pragma unroll
;     for (int db = 0; db < 2; ++db)
; #pragma unroll
;         for (int g = 0; g < 4; ++g) { const int c = 32 * db + 8 * g + 4 * hi; const u32x2 z = zv[4 * db + g];
;             const f32x16& o = db ? st.o1 : st.o0;
;             u32x2 w; w.x = cvt_pk_bf16(o[4 * g] * inv * silu_f(bf_lo(z.x)), o[4 * g + 1] * inv * silu_f(bf_hi(z.x)));
;             w.y = cvt_pk_bf16(o[4 * g + 2] * inv * silu_f(bf_lo(z.y)), o[4 * g + 3] * inv * silu_f(bf_hi(z.y)));
;             *(u32x2*)(yrow + c) = w; }
; __global__ void __launch_bounds__(NWAVES * 64, 2) mk_fwd(Args args) {
;     ...
;                 la_loadz(zv, PROJ + (size_t)tqa * PP + C_ZD + h * 64, hi); la_store(sa, false, 0.f, zv, Yb + (size_t)tqa * DMODEL + 1536 + h * 64, hi);
;                 la_loadz(zv, PROJ + (size_t)tqb * PP + C_ZD + h * 64, hi); la_store(sb, false, 0.f, zv, Yb + (size_t)tqb * DMODEL + 1536 + h * 64, hi);
;             }
;             __syncthreads();
	v_lshlrev_b32_e32 v0, 16, v24
	v_and_b32_e32 v1, 0xffff0000, v24
	v_mul_f32_e32 v2, 0xbfb8aa3b, v0
	v_mul_f32_e32 v3, 0xbfb8aa3b, v1
	v_exp_f32_e32 v2, v2
	v_exp_f32_e32 v3, v3
	v_add_f32_e32 v2, 1.0, v2
	v_add_f32_e32 v3, 1.0, v3
	v_rcp_f32_e32 v2, v2
	v_rcp_f32_e32 v3, v3
	s_nop 0
	v_pk_mul_f32 v[0:1], v[2:3], v[0:1]
	s_nop 0
	v_pk_mul_f32 v[0:1], v[4:5], v[0:1]
	v_lshlrev_b32_e32 v2, 16, v25
	v_cvt_pk_bf16_f32 v0, v0, v1
	v_mul_f32_e32 v1, 0xbfb8aa3b, v2
	v_exp_f32_e32 v1, v1
	v_and_b32_e32 v3, 0xffff0000, v25
	v_add_f32_e32 v1, 1.0, v1
	v_rcp_f32_e32 v4, v1
	v_mul_f32_e32 v1, 0xbfb8aa3b, v3
	v_exp_f32_e32 v1, v1
	s_nop 0
	v_add_f32_e32 v1, 1.0, v1
	v_rcp_f32_e32 v5, v1
	s_nop 0
	v_pk_mul_f32 v[2:3], v[4:5], v[2:3]
	s_nop 0
	v_pk_mul_f32 v[2:3], v[6:7], v[2:3]
	v_pk_mul_f32 v[4:5], v[8:9], v[18:19] op_sel_hi:[1,0]
	v_cvt_pk_bf16_f32 v1, v2, v3
	global_store_dwordx2 v[20:21], v[0:1], off offset:3152
	s_waitcnt vmcnt(7)
	v_lshlrev_b32_e32 v0, 16, v22
	v_and_b32_e32 v1, 0xffff0000, v22
	v_mul_f32_e32 v2, 0xbfb8aa3b, v0
	v_mul_f32_e32 v3, 0xbfb8aa3b, v1
	v_exp_f32_e32 v2, v2
	v_exp_f32_e32 v3, v3
	v_pk_mul_f32 v[6:7], v[10:11], v[18:19] op_sel_hi:[1,0]
	v_add_f32_e32 v2, 1.0, v2
	v_add_f32_e32 v3, 1.0, v3
	v_rcp_f32_e32 v2, v2
	v_rcp_f32_e32 v3, v3
	s_nop 0
	v_pk_mul_f32 v[0:1], v[2:3], v[0:1]
	s_nop 0
	v_pk_mul_f32 v[0:1], v[4:5], v[0:1]
	v_lshlrev_b32_e32 v2, 16, v23
	v_cvt_pk_bf16_f32 v0, v0, v1
	v_mul_f32_e32 v1, 0xbfb8aa3b, v2
	v_exp_f32_e32 v1, v1
	v_and_b32_e32 v3, 0xffff0000, v23
	v_add_f32_e32 v1, 1.0, v1
	v_rcp_f32_e32 v4, v1
	v_mul_f32_e32 v1, 0xbfb8aa3b, v3
	v_exp_f32_e32 v1, v1
	s_nop 0
	v_add_f32_e32 v1, 1.0, v1
	v_rcp_f32_e32 v5, v1
	s_nop 0
	v_pk_mul_f32 v[2:3], v[4:5], v[2:3]
	s_nop 0
	v_pk_mul_f32 v[2:3], v[6:7], v[2:3]
	v_pk_mul_f32 v[4:5], v[12:13], v[18:19] op_sel_hi:[1,0]
	v_cvt_pk_bf16_f32 v1, v2, v3
	global_store_dwordx2 v[20:21], v[0:1], off offset:3168
	s_waitcnt vmcnt(7)
	v_lshlrev_b32_e32 v0, 16, v16
	v_and_b32_e32 v1, 0xffff0000, v16
	v_mul_f32_e32 v2, 0xbfb8aa3b, v0
	v_mul_f32_e32 v3, 0xbfb8aa3b, v1
	v_exp_f32_e32 v2, v2
	v_exp_f32_e32 v3, v3
	v_pk_mul_f32 v[6:7], v[14:15], v[18:19] op_sel_hi:[1,0]
	v_add_f32_e32 v2, 1.0, v2
	v_add_f32_e32 v3, 1.0, v3
	v_rcp_f32_e32 v2, v2
	v_rcp_f32_e32 v3, v3
	s_nop 0
	v_pk_mul_f32 v[0:1], v[2:3], v[0:1]
	s_nop 0
	v_pk_mul_f32 v[0:1], v[4:5], v[0:1]
	v_lshlrev_b32_e32 v2, 16, v17
	v_cvt_pk_bf16_f32 v0, v0, v1
	v_mul_f32_e32 v1, 0xbfb8aa3b, v2
	v_exp_f32_e32 v1, v1
	v_and_b32_e32 v3, 0xffff0000, v17
	v_add_f32_e32 v1, 1.0, v1
	v_rcp_f32_e32 v4, v1
	v_mul_f32_e32 v1, 0xbfb8aa3b, v3
	v_exp_f32_e32 v1, v1
	s_nop 0
	v_add_f32_e32 v1, 1.0, v1
	v_rcp_f32_e32 v5, v1
	s_nop 0
	v_pk_mul_f32 v[2:3], v[4:5], v[2:3]
	s_nop 0
	v_pk_mul_f32 v[2:3], v[6:7], v[2:3]
	s_nop 0
	v_cvt_pk_bf16_f32 v1, v2, v3
	global_store_dwordx2 v[20:21], v[0:1], off offset:3184
	v_readlane_b32 s100, v255, 44
	s_lshl_b32 s100, s100, 3
	s_lshr_b32 s101, s69, 6
	s_add_i32 s100, s100, s101
	s_lshl_b32 s100, s100, 12
	s_lshl_b32 s101, s68, 23
	s_add_i32 s100, s100, s101
	s_add_u32 s98, s48, 0x7000000
	s_addc_u32 s99, s49, 0
	s_add_u32 s98, s98, s100
	s_addc_u32 s99, s99, 0
	v_lshlrev_b32_e32 v227, 4, v252
	global_load_dwordx4 v[228:231], v227, s[98:99]
	global_load_dwordx4 v[228:231], v227, s[98:99] offset:1024
	global_load_dwordx4 v[228:231], v227, s[98:99] offset:2048
	global_load_dwordx4 v[228:231], v227, s[98:99] offset:3072
	s_barrier
